# EA on all units with the S1 delay reduced to 2 sleeps
# baseline (speedup 1.0000x reference)
; #define PG8_STAGE(bufoff, gbase, voff) do { _Pragma("unroll") for (int _i = 0; _i < 2; ++_i) \
;         __builtin_amdgcn_global_load_lds((const unsigned*)((const char*)(gbase) + (voff)[_i]), (LAS unsigned*)(lds + (bufoff) + ldsw + _i * 8192), 16, 0, 0); } while (0)
; #define PG8_WAIT_V(n) asm volatile("s_waitcnt vmcnt(" #n ")" ::: "memory")
; #define PG8_BAR __builtin_amdgcn_s_barrier()
; __device__ __forceinline__ bool gemm_phase(LAS unsigned char* lds, int l, int sub, int gi, bool dry = false) {
;     ...
;     Unit cur, nxt; int ui = 0;
;     if (!unit_next(g, 0, cur)) return true;
;     f32x4 acc[2][2][4][2];
; #pragma unroll
;     for (int a = 0; a < 2; ++a)
; #pragma unroll
;         for (int b = 0; b < 2; ++b)
; #pragma unroll
;             for (int m = 0; m < 4; ++m)
; #pragma unroll
;                 for (int n = 0; n < 2; ++n) acc[a][b][m][n] = (f32x4){0.f, 0.f, 0.f, 0.f};
;     bf16x8 At[4][2], B0[2][2], B1[2][2];
;     const char* cA = (const char*)g.A + (size_t)cur.pm * tstepA + (size_t)cur.k0 * kstep; const char* cB = (const char*)g.Bt + (size_t)cur.pn * tstepB + (size_t)cur.k0 * kstep;
;     PG8_STAGE(PG8_SB(0, 0), cB, voffB); PG8_STAGE(PG8_SA(0, 0), cA, voffA); PG8_STAGE(PG8_SB(0, 1), cB + hstepB, voffB); PG8_STAGE(PG8_SA(0, 1), cA + hstepA, voffA);
;     if (wr == 1) PG8_BAR;
;     PG8_WAIT_V(4); PG8_BAR;
;     PG8_STAGE(PG8_SB(1, 0), cB + kstep, voffB); PG8_STAGE(PG8_SA(1, 0), cA + kstep, voffA); PG8_STAGE(PG8_SB(1, 1), cB + hstepB + kstep, voffB);
;     PG8_WAIT_V(6); PG8_BAR;
.LBB0_243:
	s_cmp_lg_u32 s59, 0
	s_cbranch_scc1 .Lmy_nodelay
	v_readlane_b32 s4, v255, 0
	s_nop 3
	s_cmp_lg_u32 s17, 6
	s_cbranch_scc1 .Lmy_dl0
	s_cmp_lg_u32 s4, 1
	s_cbranch_scc1 .Lmy_dl0
	s_cmp_lt_u32 s26, 128
	s_cbranch_scc1 .Lmy_nodelay
	s_sleep 127
	s_sleep 127
	s_branch .Lmy_nodelay
